# sample attention prologue: three split-K partial-sum groups in flight instead of two (acc3) on top of fold
# baseline (speedup 1.0000x reference)
; __device__ __forceinline__ f32x4 acc1_4(const float* ACC1, int srow, int col) {
;     f32x4 s = *(const f32x4*)(ACC1 + (size_t)srow * N1 + col);
; #pragma unroll
;     for (int kp = 1; kp < 8; ++kp) s += *(const f32x4*)(ACC1 + ((size_t)kp * TS + srow) * N1 + col);
;     return s;
; __device__ __forceinline__ void attn_sample_item(const P& p, int wi, int lane) {
;     ...
;     const int srow = bs * 4 + i;
;     const float* ACC1 = (const float*)(ws + O_ACC1); const float* rstd1 = (const float*)(ws + O_RSTD1);
;     float q[8];
;     { const float rq = rstd1[TP + srow] * (0.08838834764831845f * LOG2E);
;       const f32x4 q0 = acc1_4(ACC1, srow, 3072 + h * 128 + 8 * li), q1 = acc1_4(ACC1, srow, 3072 + h * 128 + 8 * li + 4);
;       q[0] = q0[0] * rq; q[1] = q0[1] * rq; q[2] = q0[2] * rq; q[3] = q0[3] * rq; q[4] = q1[0] * rq; q[5] = q1[1] * rq; q[6] = q1[2] * rq; q[7] = q1[3] * rq; }
;     if (kg == 0) {
;         const float rs = rstd1[TP + srow];
;         float* ko = p.out + OUT_KN + (size_t)srow * 1024 + h * 128 + 8 * li; float* vo = p.out + OUT_VN + (size_t)srow * 1024 + h * 128 + 8 * li;
;         *(f32x4*)ko = acc1_4(ACC1, srow, 4096 + h * 128 + 8 * li) * rs; *(f32x4*)(ko + 4) = acc1_4(ACC1, srow, 4096 + h * 128 + 8 * li + 4) * rs;
;         *(f32x4*)vo = acc1_4(ACC1, srow, 5120 + h * 128 + 8 * li) * rs; *(f32x4*)(vo + 4) = acc1_4(ACC1, srow, 5120 + h * 128 + 8 * li + 4) * rs;
.Las_item:
	s_ashr_i32 s14, s3, 5
	s_bfe_u32 s15, s3, 0x20003
	s_and_b32 s16, s3, 7
	s_lshl_b32 s17, s14, 2
	s_or_b32 s17, s17, s15
	s_lshl_b32 s18, s14, 23
	s_add_u32 s20, s56, s18
	s_addc_u32 s21, s57, 0
	s_add_u32 s24, s58, s18
	s_addc_u32 s25, s59, 0
	s_lshl_b32 s18, s17, 2
	s_add_u32 s18, s18, 0x8000
	s_load_dword s19, s[10:11], s18
	s_lshl_b32 s23, s16, 9
	v_and_b32_e32 v72, 15, v230
	v_lshlrev_b32_e32 v72, 4, v72
	v_bfe_u32 v73, v230, 4, 2
	v_cvt_f32_u32_e32 v202, v73
	v_add_u32_e32 v72, s23, v72
	s_add_u32 s43, s15, 0x800
	s_lshl_b32 s43, s43, 12
	v_add_u32_e32 v203, s43, v72
	s_sub_u32 s43, 0x7a, s16
	s_lshl_b32 s43, s43, 23
	v_mov_b32_e32 v201, s43
	v_mul_f32_e32 v201, 0xbfb8aa3b, v201
	s_mul_i32 s43, s17, 0x6000
	s_add_u32 s43, s43, 0x3000
	v_add_u32_e32 v64, s43, v72
	v_sub_u32_e32 v67, s15, v73
	v_max_i32_e32 v67, 0, v67
	v_lshl_add_u32 v67, s14, 2, v67
	v_lshlrev_b32_e32 v66, 2, v67
	v_add_u32_e32 v66, 0x8000, v66
	v_mul_u32_u24_e32 v65, 0x6000, v67
	v_add_u32_e32 v65, 0x4000, v65
	v_add_u32_e32 v65, v65, v72
	v_lshlrev_b32_e32 v68, 12, v73
	v_sub_u32_e32 v68, v203, v68
	s_mov_b32 s43, 0x7ff000
	v_add_u32_e32 v69, s43, v72
	v_min_u32_e32 v68, v68, v69
	v_add_u32_e32 v69, 0xfff80000, v203
	global_load_dword v70, v66, s[10:11]
	global_load_dwordx4 v[128:131], v68, s[20:21]
	global_load_dwordx4 v[132:135], v68, s[20:21] offset:256
	global_load_dwordx4 v[136:139], v68, s[24:25]
	global_load_dwordx4 v[140:143], v68, s[24:25] offset:256
	global_load_dwordx4 v[144:147], v69, s[20:21]
	global_load_dwordx4 v[148:151], v69, s[20:21] offset:256
	global_load_dwordx4 v[152:155], v69, s[24:25]
	global_load_dwordx4 v[156:159], v69, s[24:25] offset:256
	v_mov_b32_e32 v71, v64
	global_load_dwordx4 v[0:3], v71, s[8:9]
	v_add_u32_e32 v71, 0x300000, v71
	global_load_dwordx4 v[4:7], v71, s[8:9]
	v_add_u32_e32 v71, 0x300000, v71
	global_load_dwordx4 v[8:11], v71, s[8:9]
	v_add_u32_e32 v71, 0x300000, v71
	global_load_dwordx4 v[12:15], v71, s[8:9]
	v_add_u32_e32 v71, 0x300000, v71
	global_load_dwordx4 v[16:19], v71, s[8:9]
	v_add_u32_e32 v71, 0x300000, v71
	global_load_dwordx4 v[20:23], v71, s[8:9]
	v_add_u32_e32 v71, 0x300000, v71
	global_load_dwordx4 v[24:27], v71, s[8:9]
	v_add_u32_e32 v71, 0x300000, v71
	global_load_dwordx4 v[28:31], v71, s[8:9]
	v_mov_b32_e32 v71, v64
	global_load_dwordx4 v[32:35], v71, s[8:9] offset:256
	v_add_u32_e32 v71, 0x300000, v71
	global_load_dwordx4 v[36:39], v71, s[8:9] offset:256
	v_add_u32_e32 v71, 0x300000, v71
	global_load_dwordx4 v[40:43], v71, s[8:9] offset:256
	v_add_u32_e32 v71, 0x300000, v71
	global_load_dwordx4 v[44:47], v71, s[8:9] offset:256
	v_add_u32_e32 v71, 0x300000, v71
	global_load_dwordx4 v[48:51], v71, s[8:9] offset:256
	v_add_u32_e32 v71, 0x300000, v71
	global_load_dwordx4 v[52:55], v71, s[8:9] offset:256
	v_add_u32_e32 v71, 0x300000, v71
	global_load_dwordx4 v[56:59], v71, s[8:9] offset:256
	v_add_u32_e32 v71, 0x300000, v71
	global_load_dwordx4 v[60:63], v71, s[8:9] offset:256
	v_mov_b32_e32 v71, v65
	global_load_dwordx4 v[76:79], v71, s[8:9]
	v_add_u32_e32 v71, 0x300000, v71
	global_load_dwordx4 v[80:83], v71, s[8:9]
	v_add_u32_e32 v71, 0x300000, v71
	global_load_dwordx4 v[84:87], v71, s[8:9]
	v_add_u32_e32 v71, 0x300000, v71
	global_load_dwordx4 v[88:91], v71, s[8:9]
	v_add_u32_e32 v71, 0x300000, v71
	global_load_dwordx4 v[92:95], v71, s[8:9]
	v_add_u32_e32 v71, 0x300000, v71
	global_load_dwordx4 v[96:99], v71, s[8:9]
	v_add_u32_e32 v71, 0x300000, v71
	global_load_dwordx4 v[100:103], v71, s[8:9]
	v_add_u32_e32 v71, 0x300000, v71
	global_load_dwordx4 v[104:107], v71, s[8:9]
	s_waitcnt vmcnt(16)
	v_add_f32_e32 v160, v0, v4
	v_add_f32_e32 v161, v1, v5
	v_add_f32_e32 v162, v2, v6
	v_add_f32_e32 v163, v3, v7
	v_add_f32_e32 v160, v160, v8
	v_add_f32_e32 v161, v161, v9
	v_add_f32_e32 v162, v162, v10
	v_add_f32_e32 v163, v163, v11
	v_add_f32_e32 v160, v160, v12
	v_add_f32_e32 v161, v161, v13
	v_add_f32_e32 v162, v162, v14
	v_add_f32_e32 v163, v163, v15
	v_add_f32_e32 v160, v160, v16
	v_add_f32_e32 v161, v161, v17
	v_add_f32_e32 v162, v162, v18
	v_add_f32_e32 v163, v163, v19
	v_add_f32_e32 v160, v160, v20
	v_add_f32_e32 v161, v161, v21
	v_add_f32_e32 v162, v162, v22
	v_add_f32_e32 v163, v163, v23
	v_add_f32_e32 v160, v160, v24
	v_add_f32_e32 v161, v161, v25
	v_add_f32_e32 v162, v162, v26
	v_add_f32_e32 v163, v163, v27
	v_add_f32_e32 v160, v160, v28
	v_add_f32_e32 v161, v161, v29
	v_add_f32_e32 v162, v162, v30
	v_add_f32_e32 v163, v163, v31
	v_mov_b32_e32 v71, v65
	global_load_dwordx4 v[0:3], v71, s[8:9] offset:256
	v_add_u32_e32 v71, 0x300000, v71
	global_load_dwordx4 v[4:7], v71, s[8:9] offset:256
	v_add_u32_e32 v71, 0x300000, v71
	global_load_dwordx4 v[8:11], v71, s[8:9] offset:256
	v_add_u32_e32 v71, 0x300000, v71
	global_load_dwordx4 v[12:15], v71, s[8:9] offset:256
	v_add_u32_e32 v71, 0x300000, v71
	global_load_dwordx4 v[16:19], v71, s[8:9] offset:256
	v_add_u32_e32 v71, 0x300000, v71
	global_load_dwordx4 v[20:23], v71, s[8:9] offset:256
	v_add_u32_e32 v71, 0x300000, v71
	global_load_dwordx4 v[24:27], v71, s[8:9] offset:256
	v_add_u32_e32 v71, 0x300000, v71
	global_load_dwordx4 v[28:31], v71, s[8:9] offset:256
	s_waitcnt vmcnt(16)
; __device__ __forceinline__ f32x4 acc1_4(const float* ACC1, int srow, int col) {
;     f32x4 s = *(const f32x4*)(ACC1 + (size_t)srow * N1 + col);
; #pragma unroll
;     for (int kp = 1; kp < 8; ++kp) s += *(const f32x4*)(ACC1 + ((size_t)kp * TS + srow) * N1 + col);
;     return s;
; __device__ __forceinline__ void attn_sample_item(const P& p, int wi, int lane) {
;     ...
;       const f32x4 q0 = acc1_4(ACC1, srow, 3072 + h * 128 + 8 * li), q1 = acc1_4(ACC1, srow, 3072 + h * 128 + 8 * li + 4);
;       q[0] = q0[0] * rq; q[1] = q0[1] * rq; q[2] = q0[2] * rq; q[3] = q0[3] * rq; q[4] = q1[0] * rq; q[5] = q1[1] * rq; q[6] = q1[2] * rq; q[7] = q1[3] * rq; }
;     if (kg == 0) {
;         const float rs = rstd1[TP + srow];
;         float* ko = p.out + OUT_KN + (size_t)srow * 1024 + h * 128 + 8 * li; float* vo = p.out + OUT_VN + (size_t)srow * 1024 + h * 128 + 8 * li;
;         *(f32x4*)ko = acc1_4(ACC1, srow, 4096 + h * 128 + 8 * li) * rs; *(f32x4*)(ko + 4) = acc1_4(ACC1, srow, 4096 + h * 128 + 8 * li + 4) * rs;
;         *(f32x4*)vo = acc1_4(ACC1, srow, 5120 + h * 128 + 8 * li) * rs; *(f32x4*)(vo + 4) = acc1_4(ACC1, srow, 5120 + h * 128 + 8 * li + 4) * rs;
	v_add_f32_e32 v164, v32, v36
	v_add_f32_e32 v165, v33, v37
	v_add_f32_e32 v166, v34, v38
	v_add_f32_e32 v167, v35, v39
	v_add_f32_e32 v164, v164, v40
	v_add_f32_e32 v165, v165, v41
	v_add_f32_e32 v166, v166, v42
	v_add_f32_e32 v167, v167, v43
	v_add_f32_e32 v164, v164, v44
	v_add_f32_e32 v165, v165, v45
	v_add_f32_e32 v166, v166, v46
	v_add_f32_e32 v167, v167, v47
	v_add_f32_e32 v164, v164, v48
	v_add_f32_e32 v165, v165, v49
	v_add_f32_e32 v166, v166, v50
	v_add_f32_e32 v167, v167, v51
	v_add_f32_e32 v164, v164, v52
	v_add_f32_e32 v165, v165, v53
	v_add_f32_e32 v166, v166, v54
	v_add_f32_e32 v167, v167, v55
	v_add_f32_e32 v164, v164, v56
	v_add_f32_e32 v165, v165, v57
	v_add_f32_e32 v166, v166, v58
	v_add_f32_e32 v167, v167, v59
	v_add_f32_e32 v164, v164, v60
	v_add_f32_e32 v165, v165, v61
	v_add_f32_e32 v166, v166, v62
	v_add_f32_e32 v167, v167, v63
	v_add_u32_e32 v71, 0x1000, v65
	global_load_dwordx4 v[32:35], v71, s[8:9]
	v_add_u32_e32 v71, 0x300000, v71
	global_load_dwordx4 v[36:39], v71, s[8:9]
	v_add_u32_e32 v71, 0x300000, v71
	global_load_dwordx4 v[40:43], v71, s[8:9]
	v_add_u32_e32 v71, 0x300000, v71
	global_load_dwordx4 v[44:47], v71, s[8:9]
	v_add_u32_e32 v71, 0x300000, v71
	global_load_dwordx4 v[48:51], v71, s[8:9]
	v_add_u32_e32 v71, 0x300000, v71
	global_load_dwordx4 v[52:55], v71, s[8:9]
	v_add_u32_e32 v71, 0x300000, v71
	global_load_dwordx4 v[56:59], v71, s[8:9]
	v_add_u32_e32 v71, 0x300000, v71
	global_load_dwordx4 v[60:63], v71, s[8:9]
	s_waitcnt vmcnt(16)
	v_add_f32_e32 v176, v76, v80
	v_add_f32_e32 v177, v77, v81
	v_add_f32_e32 v178, v78, v82
	v_add_f32_e32 v179, v79, v83
	v_add_f32_e32 v176, v176, v84
	v_add_f32_e32 v177, v177, v85
	v_add_f32_e32 v178, v178, v86
	v_add_f32_e32 v179, v179, v87
	v_add_f32_e32 v176, v176, v88
	v_add_f32_e32 v177, v177, v89
	v_add_f32_e32 v178, v178, v90
	v_add_f32_e32 v179, v179, v91
	v_add_f32_e32 v176, v176, v92
	v_add_f32_e32 v177, v177, v93
	v_add_f32_e32 v178, v178, v94
	v_add_f32_e32 v179, v179, v95
	v_add_f32_e32 v176, v176, v96
	v_add_f32_e32 v177, v177, v97
	v_add_f32_e32 v178, v178, v98
	v_add_f32_e32 v179, v179, v99
	v_add_f32_e32 v176, v176, v100
	v_add_f32_e32 v177, v177, v101
	v_add_f32_e32 v178, v178, v102
	v_add_f32_e32 v179, v179, v103
	v_add_f32_e32 v176, v176, v104
	v_add_f32_e32 v177, v177, v105
	v_add_f32_e32 v178, v178, v106
	v_add_f32_e32 v179, v179, v107
	v_add_u32_e32 v71, 0x1000, v65
	global_load_dwordx4 v[76:79], v71, s[8:9] offset:256
	v_add_u32_e32 v71, 0x300000, v71
	global_load_dwordx4 v[80:83], v71, s[8:9] offset:256
	v_add_u32_e32 v71, 0x300000, v71
	global_load_dwordx4 v[84:87], v71, s[8:9] offset:256
	v_add_u32_e32 v71, 0x300000, v71
	global_load_dwordx4 v[88:91], v71, s[8:9] offset:256
	v_add_u32_e32 v71, 0x300000, v71
	global_load_dwordx4 v[92:95], v71, s[8:9] offset:256
	v_add_u32_e32 v71, 0x300000, v71
	global_load_dwordx4 v[96:99], v71, s[8:9] offset:256
	v_add_u32_e32 v71, 0x300000, v71
	global_load_dwordx4 v[100:103], v71, s[8:9] offset:256
	v_add_u32_e32 v71, 0x300000, v71
	global_load_dwordx4 v[104:107], v71, s[8:9] offset:256
	s_waitcnt vmcnt(16)
	v_add_f32_e32 v180, v0, v4
	v_add_f32_e32 v181, v1, v5
	v_add_f32_e32 v182, v2, v6
	v_add_f32_e32 v183, v3, v7
	v_add_f32_e32 v180, v180, v8
	v_add_f32_e32 v181, v181, v9
	v_add_f32_e32 v182, v182, v10
	v_add_f32_e32 v183, v183, v11
	v_add_f32_e32 v180, v180, v12
	v_add_f32_e32 v181, v181, v13
	v_add_f32_e32 v182, v182, v14
	v_add_f32_e32 v183, v183, v15
	v_add_f32_e32 v180, v180, v16
	v_add_f32_e32 v181, v181, v17
	v_add_f32_e32 v182, v182, v18
	v_add_f32_e32 v183, v183, v19
	v_add_f32_e32 v180, v180, v20
	v_add_f32_e32 v181, v181, v21
	v_add_f32_e32 v182, v182, v22
	v_add_f32_e32 v183, v183, v23
	v_add_f32_e32 v180, v180, v24
	v_add_f32_e32 v181, v181, v25
	v_add_f32_e32 v182, v182, v26
	v_add_f32_e32 v183, v183, v27
	v_add_f32_e32 v180, v180, v28
	v_add_f32_e32 v181, v181, v29
	v_add_f32_e32 v182, v182, v30
	v_add_f32_e32 v183, v183, v31
	s_waitcnt vmcnt(8)
	v_add_f32_e32 v184, v32, v36
	v_add_f32_e32 v185, v33, v37
	v_add_f32_e32 v186, v34, v38
	v_add_f32_e32 v187, v35, v39
	v_add_f32_e32 v184, v184, v40
	v_add_f32_e32 v185, v185, v41
	v_add_f32_e32 v186, v186, v42
	v_add_f32_e32 v187, v187, v43
	v_add_f32_e32 v184, v184, v44
	v_add_f32_e32 v185, v185, v45
	v_add_f32_e32 v186, v186, v46
	v_add_f32_e32 v187, v187, v47
	v_add_f32_e32 v184, v184, v48
	v_add_f32_e32 v185, v185, v49
	v_add_f32_e32 v186, v186, v50
	v_add_f32_e32 v187, v187, v51
	v_add_f32_e32 v184, v184, v52
	v_add_f32_e32 v185, v185, v53
	v_add_f32_e32 v186, v186, v54
	v_add_f32_e32 v187, v187, v55
	v_add_f32_e32 v184, v184, v56
	v_add_f32_e32 v185, v185, v57
	v_add_f32_e32 v186, v186, v58
	v_add_f32_e32 v187, v187, v59
	v_add_f32_e32 v184, v184, v60
	v_add_f32_e32 v185, v185, v61
	v_add_f32_e32 v186, v186, v62
	v_add_f32_e32 v187, v187, v63
	s_waitcnt vmcnt(0)
; __device__ __forceinline__ float fexp2(float x) { return __builtin_amdgcn_exp2f(x); }
; __device__ __forceinline__ void attn_sample_item(const P& p, int wi, int lane) {
;     ...
;         const float rs = rstd1[TP + srow];
;         float* ko = p.out + OUT_KN + (size_t)srow * 1024 + h * 128 + 8 * li; float* vo = p.out + OUT_VN + (size_t)srow * 1024 + h * 128 + 8 * li;
;         *(f32x4*)ko = acc1_4(ACC1, srow, 4096 + h * 128 + 8 * li) * rs; *(f32x4*)(ko + 4) = acc1_4(ACC1, srow, 4096 + h * 128 + 8 * li + 4) * rs;
;         *(f32x4*)vo = acc1_4(ACC1, srow, 5120 + h * 128 + 8 * li) * rs; *(f32x4*)(vo + 4) = acc1_4(ACC1, srow, 5120 + h * 128 + 8 * li + 4) * rs;
;     }
;     float m = -1e30f, l = 0.f, acc[8];
; #pragma unroll
;     for (int e = 0; e < 8; ++e) acc[e] = 0.f;
;     const float sl = fexp2(-(float)(h + 1)) * LOG2E;
;     for (int g = 0; g < 3; ++g) {
;         const int d = 1 << (2 * g);
; #pragma unroll 3
;         for (int jj = 0; jj < 33; ++jj) {
;             const int j = 4 * jj + kg; const bool valid = j <= 128; const int jc = valid ? j : 128;
;             const int idx = 2048 + i - d * jc;
;             f32x4 k0, k1, v0, v1;
;             if (idx < 2048) { const size_t off = (((size_t)bs * 2048 + idx) * 8 + h) * 128 + 8 * li;
;                 k0 = __builtin_nontemporal_load((const f32x4*)(p.cache_k + off)); k1 = __builtin_nontemporal_load((const f32x4*)(p.cache_k + off + 4)); v0 = __builtin_nontemporal_load((const f32x4*)(p.cache_v + off)); v1 = __builtin_nontemporal_load((const f32x4*)(p.cache_v + off + 4)); }
;             else { const int nr = bs * 4 + (idx - 2048); const float rsn = rstd1[TP + nr]; const int c0 = 4096 + h * 128 + 8 * li;
;                 k0 = acc1_4(ACC1, nr, c0) * rsn; k1 = acc1_4(ACC1, nr, c0 + 4) * rsn; v0 = acc1_4(ACC1, nr, c0 + 1024) * rsn; v1 = acc1_4(ACC1, nr, c0 + 1028) * rsn; }
	v_add_f32_e32 v188, v76, v80
	v_add_f32_e32 v189, v77, v81
	v_add_f32_e32 v190, v78, v82
	v_add_f32_e32 v191, v79, v83
	v_add_f32_e32 v188, v188, v84
	v_add_f32_e32 v189, v189, v85
	v_add_f32_e32 v190, v190, v86
	v_add_f32_e32 v191, v191, v87
	v_add_f32_e32 v188, v188, v88
	v_add_f32_e32 v189, v189, v89
	v_add_f32_e32 v190, v190, v90
	v_add_f32_e32 v191, v191, v91
	v_add_f32_e32 v188, v188, v92
	v_add_f32_e32 v189, v189, v93
	v_add_f32_e32 v190, v190, v94
	v_add_f32_e32 v191, v191, v95
	v_add_f32_e32 v188, v188, v96
	v_add_f32_e32 v189, v189, v97
	v_add_f32_e32 v190, v190, v98
	v_add_f32_e32 v191, v191, v99
	v_add_f32_e32 v188, v188, v100
	v_add_f32_e32 v189, v189, v101
	v_add_f32_e32 v190, v190, v102
	v_add_f32_e32 v191, v191, v103
	v_add_f32_e32 v188, v188, v104
	v_add_f32_e32 v189, v189, v105
	v_add_f32_e32 v190, v190, v106
	v_add_f32_e32 v191, v191, v107
	s_waitcnt lgkmcnt(0)
	v_mov_b32_e32 v71, s19
	v_mul_f32_e32 v71, 0x3e0293ee, v71
	v_mul_f32_e32 v160, v160, v71
	v_mul_f32_e32 v161, v161, v71
	v_mul_f32_e32 v162, v162, v71
	v_mul_f32_e32 v163, v163, v71
	v_mul_f32_e32 v164, v164, v71
	v_mul_f32_e32 v165, v165, v71
	v_mul_f32_e32 v166, v166, v71
	v_mul_f32_e32 v167, v167, v71
	v_mul_f32_e32 v176, v176, v70
	v_mul_f32_e32 v177, v177, v70
	v_mul_f32_e32 v178, v178, v70
	v_mul_f32_e32 v179, v179, v70
	v_mul_f32_e32 v180, v180, v70
	v_mul_f32_e32 v181, v181, v70
	v_mul_f32_e32 v182, v182, v70
	v_mul_f32_e32 v183, v183, v70
	v_mul_f32_e32 v184, v184, v70
	v_mul_f32_e32 v185, v185, v70
	v_mul_f32_e32 v186, v186, v70
	v_mul_f32_e32 v187, v187, v70
	v_mul_f32_e32 v188, v188, v70
	v_mul_f32_e32 v189, v189, v70
	v_mul_f32_e32 v190, v190, v70
	v_mul_f32_e32 v191, v191, v70
	s_lshl_b32 s43, s17, 12
	v_add_u32_e32 v71, s43, v72
	s_mov_b64 exec, 0xffff
	global_store_dwordx4 v71, v[176:179], s[26:27]
	global_store_dwordx4 v71, v[180:183], s[26:27] offset:256
	global_store_dwordx4 v71, v[184:187], s[28:29]
	global_store_dwordx4 v71, v[188:191], s[28:29] offset:256
	s_mov_b64 exec, -1
	v_cmp_ge_u32_e32 vcc, s15, v73
	s_nop 1
	v_cndmask_b32_e32 v128, v128, v176, vcc
	v_cndmask_b32_e32 v129, v129, v177, vcc
	v_cndmask_b32_e32 v130, v130, v178, vcc
	v_cndmask_b32_e32 v131, v131, v179, vcc
	v_cndmask_b32_e32 v132, v132, v180, vcc
	v_cndmask_b32_e32 v133, v133, v181, vcc
	v_cndmask_b32_e32 v134, v134, v182, vcc
	v_cndmask_b32_e32 v135, v135, v183, vcc
	v_cndmask_b32_e32 v136, v136, v184, vcc
	v_cndmask_b32_e32 v137, v137, v185, vcc
	v_cndmask_b32_e32 v138, v138, v186, vcc
	v_cndmask_b32_e32 v139, v139, v187, vcc
	v_cndmask_b32_e32 v140, v140, v188, vcc
	v_cndmask_b32_e32 v141, v141, v189, vcc
	v_cndmask_b32_e32 v142, v142, v190, vcc
	v_cndmask_b32_e32 v143, v143, v191, vcc
	v_bfe_u32 v183, v230, 4, 2
	v_lshlrev_b32_e32 v195, 12, v183
	v_sub_u32_e32 v195, v203, v195
	s_mov_b32 s42, 0xffffc000
	v_add_u32_e32 v195, s42, v195
	global_load_dwordx4 v[16:19], v195, s[20:21]
	global_load_dwordx4 v[20:23], v195, s[20:21] offset:256
	global_load_dwordx4 v[24:27], v195, s[24:25]
	global_load_dwordx4 v[28:31], v195, s[24:25] offset:256
	v_add_u32_e32 v195, s42, v195
	global_load_dwordx4 v[32:35], v195, s[20:21]
	global_load_dwordx4 v[36:39], v195, s[20:21] offset:256
	global_load_dwordx4 v[40:43], v195, s[24:25]
	global_load_dwordx4 v[44:47], v195, s[24:25] offset:256
	v_add_u32_e32 v195, s42, v195
	global_load_dwordx4 v[48:51], v195, s[20:21]
	global_load_dwordx4 v[52:55], v195, s[20:21] offset:256
	global_load_dwordx4 v[56:59], v195, s[24:25]
	global_load_dwordx4 v[60:63], v195, s[24:25] offset:256
	v_add_u32_e32 v195, s42, v195
	global_load_dwordx4 v[64:67], v195, s[20:21]
	global_load_dwordx4 v[68:71], v195, s[20:21] offset:256
	global_load_dwordx4 v[72:75], v195, s[24:25]
	global_load_dwordx4 v[76:79], v195, s[24:25] offset:256
	v_add_u32_e32 v195, s42, v195
	global_load_dwordx4 v[80:83], v195, s[20:21]
	global_load_dwordx4 v[84:87], v195, s[20:21] offset:256
	global_load_dwordx4 v[88:91], v195, s[24:25]
	global_load_dwordx4 v[92:95], v195, s[24:25] offset:256
	v_add_u32_e32 v195, s42, v195
	global_load_dwordx4 v[96:99], v195, s[20:21]
	global_load_dwordx4 v[100:103], v195, s[20:21] offset:256
	global_load_dwordx4 v[104:107], v195, s[24:25]
	global_load_dwordx4 v[108:111], v195, s[24:25] offset:256
	v_add_u32_e32 v195, s42, v195
	global_load_dwordx4 v[112:115], v195, s[20:21]
	global_load_dwordx4 v[116:119], v195, s[20:21] offset:256
	global_load_dwordx4 v[120:123], v195, s[24:25]
	global_load_dwordx4 v[124:127], v195, s[24:25] offset:256
	v_add_u32_e32 v195, s42, v195
	global_load_dwordx4 v[0:3], v195, s[20:21]
	global_load_dwordx4 v[4:7], v195, s[20:21] offset:256
	global_load_dwordx4 v[8:11], v195, s[24:25]
	global_load_dwordx4 v[12:15], v195, s[24:25] offset:256
	v_lshlrev_b32_e32 v176, 14, v183
	v_sub_u32_e32 v176, v203, v176
	v_add_u32_e32 v176, 0xfff8c000, v176
	v_lshlrev_b32_e32 v177, 16, v183
	v_sub_u32_e32 v177, v203, v177
	v_add_u32_e32 v177, 0xffe30000, v177
	v_add_f32_e32 v182, 0x42040000, v202
	v_mul_f32_e32 v182, v182, v201
	v_mul_f32_e32 v178, 4.0, v182
	v_mul_f32_e32 v179, 16.0, v182
	v_mul_f32_e32 v180, 16.0, v201
	v_mul_f32_e32 v181, 64.0, v201
	v_mul_f32_e32 v196, 4.0, v201
	v_mov_b32_e32 v187, 0
	v_cmp_eq_u32_e32 vcc, 0, v183
	v_mov_b32_e32 v188, 0x3d800000
	s_nop 1
	v_cndmask_b32_e32 v185, v187, v188, vcc
	v_mov_b32_e32 v188, 0x3dcae00d
	v_cndmask_b32_e32 v184, v187, v188, vcc
	v_cmp_eq_u32_e32 vcc, 3, v183
	v_mov_b32_e32 v188, 0x3d800000
	s_nop 1
	v_cndmask_b32_e32 v186, v187, v188, vcc
	s_bitcmp1_b32 s2, 4
	s_cbranch_scc0 .Las_noswap
	v_swap_b32 v176, v177
	v_swap_b32 v178, v179
	v_swap_b32 v180, v181
	v_swap_b32 v186, v187
